# attention QK chains: merged per-pair lgkmcnt waits (7 fewer s_waitcnt per tile) on top of v_n9
# speedup vs baseline: 1.0075x; 1.0075x over previous
; __device__ __forceinline__ int crow(int r, int hi) { return (r & 3) + 8 * (r >> 2) + 4 * hi; }
; __device__ __forceinline__ void sb_half(f32x16& pz, float& run, bool need_mask, int kb, int t, int hi) {
;     ...
;   for (int r = 0; r < 16; ++r) {
;     const float e = __builtin_amdgcn_exp2f(fminf(pz[r] * C2, 60.f));
;     l[r] = __builtin_amdgcn_rcpf(1.f + e);
;     pz[r] = e;
;   }
;   if (need_mask) {
; #pragma unroll
;     for (int r = 0; r < 16; ++r) { if (kb + crow(r, hi) >= t) { l[r] = 1.f; pz[r] = 0.f; } }
;   }
; __device__ __forceinline__ void attn_phase(const Params& p, char* smem, int bid, int nblk) {
;     ...
;         if (k0 + 32 <= tmax) {
;           f32x16 pz;
; #pragma unroll
;           for (int r = 0; r < 16; ++r) pz[r] = 0.f;
; #pragma unroll
;           for (int d0 = 0; d0 < 8; ++d0) {
;             const bf16x8 kf = *(const bf16x8*)(K_lds + KSWZ(32 + r32, (d0 * 16 + hi * 8) * 2));
;             pz = __builtin_amdgcn_mfma_f32_32x32x16_bf16(kf, qr[d0], pz, 0, 0, 0);
;           }
;           sb_half(pz, run, k0 + 63 >= tmin, k0 + 32, t, hi);
.LBB0_1790:
	s_sub_i32 s0, s55, 63
	s_lshl_b32 s56, s53, 15
	v_cmp_le_i32_e32 vcc, s0, v173
	s_and_saveexec_b64 s[44:45], vcc
	s_cbranch_execz .LBB0_1802
	s_sub_i32 s0, s55, 31
	v_add_u32_e32 v64, s56, v194
	v_cmp_le_i32_e32 vcc, s0, v173
	v_add_u32_e32 v186, v64, v205
	v_add_u32_e32 v185, v64, v206
	v_add_u32_e32 v184, v64, v207
	v_add_u32_e32 v183, v64, v208
	v_add_u32_e32 v182, v64, v209
	v_add_u32_e32 v181, v64, v210
	v_add_u32_e32 v180, v64, v211
	v_add_u32_e32 v175, v64, v212
	s_and_saveexec_b64 s[48:49], vcc
	s_cbranch_execz .Lattn_zero
	ds_read_b128 v[64:67], v186 offset:8192
	ds_read_b128 v[144:147], v185 offset:8192
	v_cmp_ge_i32_e32 vcc, s55, v230
	s_waitcnt lgkmcnt(0)
	v_mfma_f32_32x32x16_bf16 v[64:79], v[64:67], v[80:83], 0
	v_mfma_f32_32x32x16_bf16 v[64:79], v[144:147], v[84:87], v[64:79]
	ds_read_b128 v[144:147], v184 offset:8192
	ds_read_b128 v[148:151], v183 offset:8192
	s_waitcnt lgkmcnt(0)
	v_mfma_f32_32x32x16_bf16 v[64:79], v[144:147], v[88:91], v[64:79]
	v_mfma_f32_32x32x16_bf16 v[64:79], v[148:151], v[92:95], v[64:79]
	ds_read_b128 v[144:147], v182 offset:8192
	ds_read_b128 v[148:151], v181 offset:8192
	s_waitcnt lgkmcnt(0)
	v_mfma_f32_32x32x16_bf16 v[64:79], v[144:147], v[96:99], v[64:79]
	v_mfma_f32_32x32x16_bf16 v[64:79], v[148:151], v[100:103], v[64:79]
	ds_read_b128 v[144:147], v180 offset:8192
	ds_read_b128 v[148:151], v175 offset:8192
	s_waitcnt lgkmcnt(0)
	v_mfma_f32_32x32x16_bf16 v[64:79], v[144:147], v[104:107], v[64:79]
	v_mfma_f32_32x32x16_bf16 v[64:79], v[148:151], v[108:111], v[64:79]
	s_nop 11
	v_mul_f32_e32 v64, 0x3e0293ee, v64
	v_mul_f32_e32 v67, 0x3e0293ee, v67
	v_mul_f32_e32 v68, 0x3e0293ee, v68
	v_mul_f32_e32 v71, 0x3e0293ee, v71
	v_min_f32_e32 v64, 0x42700000, v64
	v_min_f32_e32 v67, 0x42700000, v67
	v_min_f32_e32 v68, 0x42700000, v68
	v_min_f32_e32 v144, 0x42700000, v71
	v_exp_f32_e32 v71, v64
	v_exp_f32_e32 v187, v67
	v_exp_f32_e32 v234, v68
	v_mul_f32_e32 v66, 0x3e0293ee, v66
	v_mul_f32_e32 v72, 0x3e0293ee, v72
	v_mul_f32_e32 v74, 0x3e0293ee, v74
	v_mul_f32_e32 v75, 0x3e0293ee, v75
	v_mul_f32_e32 v76, 0x3e0293ee, v76
	v_min_f32_e32 v66, 0x42700000, v66
	v_min_f32_e32 v72, 0x42700000, v72
	v_mul_f32_e32 v70, 0x3e0293ee, v70
	v_mul_f32_e32 v73, 0x3e0293ee, v73
	v_mul_f32_e32 v77, 0x3e0293ee, v77
	v_min_f32_e32 v74, 0x42700000, v74
	v_min_f32_e32 v75, 0x42700000, v75
	v_min_f32_e32 v76, 0x42700000, v76
	v_exp_f32_e32 v178, v66
	v_exp_f32_e32 v235, v72
	v_add_f32_e32 v66, 1.0, v71
	v_add_f32_e32 v72, 1.0, v187
	v_mul_f32_e32 v65, 0x3e0293ee, v65
	v_min_f32_e32 v70, 0x42700000, v70
	v_min_f32_e32 v145, 0x42700000, v73
	v_min_f32_e32 v77, 0x42700000, v77
	v_exp_f32_e32 v231, v144
	v_exp_f32_e32 v64, v74
	v_exp_f32_e32 v232, v75
	v_exp_f32_e32 v237, v76
	v_add_f32_e32 v75, 1.0, v234
	v_rcp_f32_e32 v74, v66
	v_rcp_f32_e32 v66, v72
	v_mul_f32_e32 v72, 0x3e0293ee, v78
	v_mul_f32_e32 v69, 0x3e0293ee, v69
	v_min_f32_e32 v65, 0x42700000, v65
	v_exp_f32_e32 v70, v70
	v_exp_f32_e32 v67, v145
	v_exp_f32_e32 v236, v77
	v_rcp_f32_e32 v77, v75
	v_min_f32_e32 v72, 0x42700000, v72
	v_mul_f32_e32 v75, 0x3e0293ee, v79
	v_min_f32_e32 v69, 0x42700000, v69
	v_exp_f32_e32 v65, v65
	v_exp_f32_e32 v72, v72
	v_min_f32_e32 v75, 0x42700000, v75
	v_exp_f32_e32 v73, v69
	v_add_f32_e32 v69, 1.0, v178
	v_exp_f32_e32 v78, v75
	v_add_f32_e32 v147, 1.0, v231
	v_rcp_f32_e32 v144, v69
	v_add_f32_e32 v69, 1.0, v237
	v_add_f32_e32 v146, 1.0, v70
	v_add_f32_e32 v148, 1.0, v235
	v_add_f32_e32 v149, 1.0, v67
	v_rcp_f32_e32 v233, v147
	v_rcp_f32_e32 v147, v69
	v_add_f32_e32 v69, 1.0, v236
	v_add_f32_e32 v68, 1.0, v65
	v_add_f32_e32 v151, 1.0, v232
	v_rcp_f32_e32 v238, v146
	v_rcp_f32_e32 v146, v148
	v_rcp_f32_e32 v148, v149
	v_rcp_f32_e32 v149, v69
	v_add_f32_e32 v69, 1.0, v72
	v_add_f32_e32 v145, 1.0, v73
	v_add_f32_e32 v150, 1.0, v64
	v_rcp_f32_e32 v76, v68
	v_rcp_f32_e32 v68, v151
	v_rcp_f32_e32 v151, v69
	v_add_f32_e32 v69, 1.0, v78
	v_rcp_f32_e32 v145, v145
	v_rcp_f32_e32 v150, v150
	v_rcp_f32_e32 v69, v69
	s_and_saveexec_b64 s[50:51], vcc
	s_cbranch_execz .LBB0_1796
	v_add_u32_e32 v75, s55, v195
	v_subrev_u32_e32 v79, 31, v75
	v_cmp_lt_i32_e32 vcc, v79, v174
	v_subrev_u32_e32 v79, 30, v75
	v_cmp_lt_i32_e64 s[0:1], v79, v174
	v_subrev_u32_e32 v79, 29, v75
	v_cmp_lt_i32_e64 s[6:7], v79, v174
	v_subrev_u32_e32 v79, 28, v75
	v_cmp_lt_i32_e64 s[8:9], v79, v174
	v_subrev_u32_e32 v79, 23, v75
	v_cmp_lt_i32_e64 s[10:11], v79, v174
	v_subrev_u32_e32 v79, 22, v75
	v_cmp_lt_i32_e64 s[12:13], v79, v174
	v_subrev_u32_e32 v79, 21, v75
	v_cmp_lt_i32_e64 s[14:15], v79, v174
	v_subrev_u32_e32 v79, 20, v75
	v_cmp_lt_i32_e64 s[16:17], v79, v174
	v_add_u32_e32 v79, -15, v75
	v_cmp_lt_i32_e64 s[18:19], v79, v174
	v_add_u32_e32 v79, -14, v75
	v_cmp_lt_i32_e64 s[20:21], v79, v174
	v_add_u32_e32 v79, -13, v75
	v_cmp_lt_i32_e64 s[22:23], v79, v174
	v_add_u32_e32 v79, -12, v75
	v_cmp_lt_i32_e64 s[24:25], v79, v174
	v_add_u32_e32 v79, -7, v75
	v_cmp_lt_i32_e64 s[26:27], v79, v174
	v_add_u32_e32 v79, -6, v75
	v_cmp_lt_i32_e64 s[28:29], v79, v174
	v_add_u32_e32 v79, -5, v75
	v_cmp_lt_i32_e64 s[30:31], v79, v174
	s_or_b64 s[28:29], s[30:31], s[28:29]
	s_or_b64 s[26:27], s[28:29], s[26:27]
	s_or_b64 s[24:25], s[26:27], s[24:25]
	s_or_b64 s[22:23], s[24:25], s[22:23]
	s_or_b64 s[20:21], s[22:23], s[20:21]
	s_or_b64 s[18:19], s[20:21], s[18:19]
	s_or_b64 s[16:17], s[18:19], s[16:17]
	s_or_b64 s[14:15], s[16:17], s[14:15]
	s_or_b64 s[12:13], s[14:15], s[12:13]
	s_or_b64 s[10:11], s[12:13], s[10:11]
	s_or_b64 s[8:9], s[10:11], s[8:9]
	s_or_b64 s[6:7], s[8:9], s[6:7]
	s_or_b64 s[0:1], s[6:7], s[0:1]
	s_or_b64 vcc, s[0:1], vcc
	v_add_u32_e32 v75, -4, v75
	v_cndmask_b32_e64 v72, 0, v72, s[30:31]
	v_cndmask_b32_e64 v236, 0, v236, s[28:29]
	v_cndmask_b32_e64 v237, 0, v237, s[26:27]
	v_cndmask_b32_e64 v232, 0, v232, s[24:25]
	v_cndmask_b32_e64 v64, 0, v64, s[22:23]
	v_cndmask_b32_e64 v67, 0, v67, s[20:21]
	v_cndmask_b32_e64 v235, 0, v235, s[18:19]
	v_cndmask_b32_e64 v231, 0, v231, s[16:17]
	v_cndmask_b32_e64 v70, 0, v70, s[14:15]
	v_cndmask_b32_e64 v73, 0, v73, s[12:13]
	v_cndmask_b32_e64 v234, 0, v234, s[10:11]
	v_cndmask_b32_e64 v187, 0, v187, s[8:9]
	v_cndmask_b32_e64 v178, 0, v178, s[6:7]
	v_cndmask_b32_e64 v65, 0, v65, s[0:1]
	v_cndmask_b32_e32 v71, 0, v71, vcc
	v_cndmask_b32_e64 v149, 1.0, v149, s[28:29]
	v_cndmask_b32_e64 v147, 1.0, v147, s[26:27]
	v_cndmask_b32_e64 v68, 1.0, v68, s[24:25]
	v_cndmask_b32_e64 v150, 1.0, v150, s[22:23]
	v_cndmask_b32_e64 v148, 1.0, v148, s[20:21]
	v_cndmask_b32_e64 v146, 1.0, v146, s[18:19]
	v_cndmask_b32_e64 v233, 1.0, v233, s[16:17]
	v_cndmask_b32_e64 v238, 1.0, v238, s[14:15]
	v_cndmask_b32_e64 v145, 1.0, v145, s[12:13]
	v_cndmask_b32_e64 v77, 1.0, v77, s[10:11]
	v_cndmask_b32_e64 v66, 1.0, v66, s[8:9]
	v_cndmask_b32_e64 v144, 1.0, v144, s[6:7]
	v_cndmask_b32_e64 v76, 1.0, v76, s[0:1]
	v_cndmask_b32_e32 v74, 1.0, v74, vcc
	v_cndmask_b32_e64 v151, 1.0, v151, s[30:31]
	v_cmp_ge_i32_e32 vcc, v75, v174
	s_and_saveexec_b64 s[0:1], vcc
	v_mov_b32_e32 v78, 0
	v_mov_b32_e32 v69, 1.0
	s_or_b64 exec, exec, s[0:1]

; __device__ __forceinline__ int crow(int r, int hi) { return (r & 3) + 8 * (r >> 2) + 4 * hi; }
; __device__ __forceinline__ void sb_half(f32x16& pz, float& run, bool need_mask, int kb, int t, int hi) {
;     ...
;   for (int r = 0; r < 16; ++r) {
;     const float e = __builtin_amdgcn_exp2f(fminf(pz[r] * C2, 60.f));
;     l[r] = __builtin_amdgcn_rcpf(1.f + e);
;     pz[r] = e;
;   }
;   if (need_mask) {
; #pragma unroll
;     for (int r = 0; r < 16; ++r) { if (kb + crow(r, hi) >= t) { l[r] = 1.f; pz[r] = 0.f; } }
;   }
; __device__ __forceinline__ void attn_phase(const Params& p, char* smem, int bid, int nblk) {
;     ...
;         {
;           f32x16 pz;
; #pragma unroll
;           for (int r = 0; r < 16; ++r) pz[r] = 0.f;
; #pragma unroll
;           for (int d0 = 0; d0 < 8; ++d0) {
;             const bf16x8 kf = *(const bf16x8*)(K_lds + KSWZ(r32, (d0 * 16 + hi * 8) * 2));
;             pz = __builtin_amdgcn_mfma_f32_32x32x16_bf16(kf, qr[d0], pz, 0, 0, 0);
;           }
;           sb_half(pz, run, k0 + 31 >= tmin, k0, t, hi);
.LBB0_1797:
	s_or_b64 exec, exec, s[48:49]
	ds_read_b128 v[64:67], v186
	ds_read_b128 v[232:235], v185
	s_sub_i32 s0, s55, 32
	v_cmp_ge_i32_e32 vcc, s0, v230
	s_waitcnt lgkmcnt(0)
	v_mfma_f32_32x32x16_bf16 v[64:79], v[64:67], v[80:83], 0
	v_mfma_f32_32x32x16_bf16 v[64:79], v[232:235], v[84:87], v[64:79]
	ds_read_b128 v[184:187], v184
	ds_read_b128 v[232:235], v183
	s_waitcnt lgkmcnt(0)
	v_mfma_f32_32x32x16_bf16 v[64:79], v[184:187], v[88:91], v[64:79]
	v_mfma_f32_32x32x16_bf16 v[64:79], v[232:235], v[92:95], v[64:79]
	ds_read_b128 v[182:185], v182
	ds_read_b128 v[232:235], v181
	s_waitcnt lgkmcnt(1)
	v_mfma_f32_32x32x16_bf16 v[64:79], v[182:185], v[96:99], v[64:79]
	ds_read_b128 v[180:183], v180
	ds_read_b128 v[184:187], v175
	s_waitcnt lgkmcnt(2)
	v_mfma_f32_32x32x16_bf16 v[64:79], v[232:235], v[100:103], v[64:79]
	s_waitcnt lgkmcnt(0)
	v_mfma_f32_32x32x16_bf16 v[64:79], v[180:183], v[104:107], v[64:79]
	v_mfma_f32_32x32x16_bf16 v[64:79], v[184:187], v[108:111], v[64:79]
	s_nop 11
	v_mul_f32_e32 v64, 0x3e0293ee, v64
	v_mul_f32_e32 v67, 0x3e0293ee, v67
	v_mul_f32_e32 v68, 0x3e0293ee, v68
	v_mul_f32_e32 v71, 0x3e0293ee, v71
	v_min_f32_e32 v64, 0x42700000, v64
	v_min_f32_e32 v67, 0x42700000, v67
	v_min_f32_e32 v68, 0x42700000, v68
	v_min_f32_e32 v180, 0x42700000, v71
	v_exp_f32_e32 v71, v64
	v_exp_f32_e32 v175, v67
	v_exp_f32_e32 v234, v68
	v_mul_f32_e32 v66, 0x3e0293ee, v66
	v_mul_f32_e32 v72, 0x3e0293ee, v72
	v_mul_f32_e32 v74, 0x3e0293ee, v74
	v_mul_f32_e32 v75, 0x3e0293ee, v75
	v_mul_f32_e32 v76, 0x3e0293ee, v76
	v_min_f32_e32 v66, 0x42700000, v66
	v_min_f32_e32 v72, 0x42700000, v72
	v_mul_f32_e32 v70, 0x3e0293ee, v70
	v_mul_f32_e32 v73, 0x3e0293ee, v73
	v_mul_f32_e32 v77, 0x3e0293ee, v77
	v_min_f32_e32 v74, 0x42700000, v74
	v_min_f32_e32 v75, 0x42700000, v75
	v_min_f32_e32 v76, 0x42700000, v76
	v_exp_f32_e32 v178, v66
	v_exp_f32_e32 v235, v72
	v_add_f32_e32 v66, 1.0, v71
	v_add_f32_e32 v72, 1.0, v175
	v_mul_f32_e32 v65, 0x3e0293ee, v65
	v_min_f32_e32 v70, 0x42700000, v70
	v_min_f32_e32 v181, 0x42700000, v73
	v_min_f32_e32 v77, 0x42700000, v77
	v_exp_f32_e32 v231, v180
	v_exp_f32_e32 v64, v74
	v_exp_f32_e32 v232, v75
	v_exp_f32_e32 v237, v76
	v_add_f32_e32 v75, 1.0, v234
	v_rcp_f32_e32 v74, v66
	v_rcp_f32_e32 v66, v72
	v_mul_f32_e32 v72, 0x3e0293ee, v78
	v_mul_f32_e32 v69, 0x3e0293ee, v69
	v_min_f32_e32 v65, 0x42700000, v65
	v_exp_f32_e32 v70, v70
	v_exp_f32_e32 v67, v181
	v_exp_f32_e32 v236, v77
	v_rcp_f32_e32 v77, v75
	v_min_f32_e32 v72, 0x42700000, v72
	v_mul_f32_e32 v75, 0x3e0293ee, v79
	v_min_f32_e32 v69, 0x42700000, v69
	v_exp_f32_e32 v65, v65
	v_exp_f32_e32 v72, v72
	v_min_f32_e32 v75, 0x42700000, v75
	v_exp_f32_e32 v73, v69
	v_add_f32_e32 v69, 1.0, v178
	v_exp_f32_e32 v78, v75
	v_add_f32_e32 v183, 1.0, v231
	v_rcp_f32_e32 v180, v69
	v_add_f32_e32 v69, 1.0, v237
	v_add_f32_e32 v182, 1.0, v70
	v_add_f32_e32 v184, 1.0, v235
	v_add_f32_e32 v185, 1.0, v67
	v_rcp_f32_e32 v233, v183
	v_rcp_f32_e32 v183, v69
	v_add_f32_e32 v69, 1.0, v236
	v_add_f32_e32 v68, 1.0, v65
	v_add_f32_e32 v187, 1.0, v232
	v_rcp_f32_e32 v238, v182
	v_rcp_f32_e32 v182, v184
	v_rcp_f32_e32 v184, v185
	v_rcp_f32_e32 v185, v69
	v_add_f32_e32 v69, 1.0, v72
	v_add_f32_e32 v181, 1.0, v73
	v_add_f32_e32 v186, 1.0, v64
	v_rcp_f32_e32 v76, v68
	v_rcp_f32_e32 v68, v187
	v_rcp_f32_e32 v187, v69
	v_add_f32_e32 v69, 1.0, v78
	v_rcp_f32_e32 v181, v181
	v_rcp_f32_e32 v186, v186
	v_rcp_f32_e32 v69, v69
	s_and_saveexec_b64 s[48:49], vcc
	s_cbranch_execz .LBB0_1801
	v_add_u32_e32 v75, s55, v195
	v_subrev_u32_e32 v79, 63, v75
	v_cmp_lt_i32_e32 vcc, v79, v174
	v_subrev_u32_e32 v79, 62, v75
	v_cmp_lt_i32_e64 s[0:1], v79, v174
	v_subrev_u32_e32 v79, 61, v75
	v_cmp_lt_i32_e64 s[6:7], v79, v174
	v_subrev_u32_e32 v79, 60, v75
	v_cmp_lt_i32_e64 s[8:9], v79, v174
	v_subrev_u32_e32 v79, 55, v75
	v_cmp_lt_i32_e64 s[10:11], v79, v174
	v_subrev_u32_e32 v79, 54, v75
	v_cmp_lt_i32_e64 s[12:13], v79, v174
	v_subrev_u32_e32 v79, 53, v75
	v_cmp_lt_i32_e64 s[14:15], v79, v174
	v_subrev_u32_e32 v79, 52, v75
	v_cmp_lt_i32_e64 s[16:17], v79, v174
	v_subrev_u32_e32 v79, 47, v75
	v_cmp_lt_i32_e64 s[18:19], v79, v174
	v_subrev_u32_e32 v79, 46, v75
	v_cmp_lt_i32_e64 s[20:21], v79, v174
	v_subrev_u32_e32 v79, 45, v75
	v_cmp_lt_i32_e64 s[22:23], v79, v174
	v_subrev_u32_e32 v79, 44, v75
	v_cmp_lt_i32_e64 s[24:25], v79, v174
	v_subrev_u32_e32 v79, 39, v75
	v_cmp_lt_i32_e64 s[26:27], v79, v174
	v_subrev_u32_e32 v79, 38, v75
	v_cmp_lt_i32_e64 s[28:29], v79, v174
	v_subrev_u32_e32 v79, 37, v75
	v_cmp_lt_i32_e64 s[30:31], v79, v174
	s_or_b64 s[28:29], s[30:31], s[28:29]
	s_or_b64 s[26:27], s[28:29], s[26:27]
	s_or_b64 s[24:25], s[26:27], s[24:25]
	s_or_b64 s[22:23], s[24:25], s[22:23]
	s_or_b64 s[20:21], s[22:23], s[20:21]
	s_or_b64 s[18:19], s[20:21], s[18:19]
	s_or_b64 s[16:17], s[18:19], s[16:17]
	s_or_b64 s[14:15], s[16:17], s[14:15]
	s_or_b64 s[12:13], s[14:15], s[12:13]
	s_or_b64 s[10:11], s[12:13], s[10:11]
	s_or_b64 s[8:9], s[10:11], s[8:9]
	s_or_b64 s[6:7], s[8:9], s[6:7]
	s_or_b64 s[0:1], s[6:7], s[0:1]
	s_or_b64 vcc, s[0:1], vcc
	v_subrev_u32_e32 v75, 36, v75
	v_cndmask_b32_e64 v72, 0, v72, s[30:31]
	v_cndmask_b32_e64 v236, 0, v236, s[28:29]
	v_cndmask_b32_e64 v237, 0, v237, s[26:27]
	v_cndmask_b32_e64 v232, 0, v232, s[24:25]
	v_cndmask_b32_e64 v64, 0, v64, s[22:23]
	v_cndmask_b32_e64 v67, 0, v67, s[20:21]
	v_cndmask_b32_e64 v235, 0, v235, s[18:19]
	v_cndmask_b32_e64 v231, 0, v231, s[16:17]
	v_cndmask_b32_e64 v70, 0, v70, s[14:15]
	v_cndmask_b32_e64 v73, 0, v73, s[12:13]
	v_cndmask_b32_e64 v234, 0, v234, s[10:11]
	v_cndmask_b32_e64 v175, 0, v175, s[8:9]
	v_cndmask_b32_e64 v178, 0, v178, s[6:7]
	v_cndmask_b32_e64 v65, 0, v65, s[0:1]
	v_cndmask_b32_e32 v71, 0, v71, vcc
	v_cndmask_b32_e64 v185, 1.0, v185, s[28:29]
	v_cndmask_b32_e64 v183, 1.0, v183, s[26:27]
	v_cndmask_b32_e64 v68, 1.0, v68, s[24:25]
	v_cndmask_b32_e64 v186, 1.0, v186, s[22:23]
	v_cndmask_b32_e64 v184, 1.0, v184, s[20:21]
	v_cndmask_b32_e64 v182, 1.0, v182, s[18:19]
	v_cndmask_b32_e64 v233, 1.0, v233, s[16:17]
	v_cndmask_b32_e64 v238, 1.0, v238, s[14:15]
	v_cndmask_b32_e64 v181, 1.0, v181, s[12:13]
	v_cndmask_b32_e64 v77, 1.0, v77, s[10:11]
	v_cndmask_b32_e64 v66, 1.0, v66, s[8:9]
	v_cndmask_b32_e64 v180, 1.0, v180, s[6:7]
	v_cndmask_b32_e64 v76, 1.0, v76, s[0:1]
	v_cndmask_b32_e32 v74, 1.0, v74, vcc
	v_cndmask_b32_e64 v187, 1.0, v187, s[30:31]
	v_cmp_ge_i32_e32 vcc, v75, v174
	s_and_saveexec_b64 s[0:1], vcc
	v_mov_b32_e32 v78, 0
	v_mov_b32_e32 v69, 1.0
	s_or_b64 exec, exec, s[0:1]
